# SGU item: all global loads (gv, stats, w_s tile) issued together into distinct registers instead of 9 serialized wait-after-load round trips
# speedup vs baseline: 1.0198x; 1.0073x over previous
; #define LAS __attribute__((address_space(3)))
; __device__ __forceinline__ unsigned pk2(float lo, float hi) { unsigned r; asm("v_cvt_pk_bf16_f32 %0, %1, %2" : "=v"(r) : "v"(lo), "v"(hi)); return r; }
; __device__ __forceinline__ float bf_lo(unsigned u) { return __uint_as_float(u << 16); }
; __device__ __forceinline__ float bf_hi(unsigned u) { return __uint_as_float(u & 0xffff0000u); }
; __device__ __forceinline__ void phase_sgu(const Params& P, LAS unsigned char* lds, int layer_i) {
;     ...
;         for (int i = 0; i < 4; ++i) { const int n = tid + 512 * i, row = n >> 4, ch = n & 15;
;             *(LAS u32x4*)(lds + SG_A + off_b(row, ch)) = *(const u32x4*)(wsb + ((size_t)g * 128 + row) * 128 + ch * 8); }
;         __syncthreads();
; #pragma unroll
;         for (int i = 0; i < 8; ++i) { const int n = tid + 512 * i, row = n >> 5, cc = n & 31, c0 = g * 256 + cc * 8;
;             const u32x4 v = gvr[i];
;             const float mu = st[2 * row], rs = st[2 * row + 1];
;             const f32x4 g0 = *(const f32x4*)(lng + c0), g1 = *(const f32x4*)(lng + c0 + 4), b0 = *(const f32x4*)(lnb + c0), b1 = *(const f32x4*)(lnb + c0 + 4);
;             u32x4 o;
;             o.x = pk2((bf_lo(v.x) - mu) * rs * g0.x + b0.x, (bf_hi(v.x) - mu) * rs * g0.y + b0.y); o.y = pk2((bf_lo(v.y) - mu) * rs * g0.z + b0.z, (bf_hi(v.y) - mu) * rs * g0.w + b0.w);
;             o.z = pk2((bf_lo(v.z) - mu) * rs * g1.x + b1.x, (bf_hi(v.z) - mu) * rs * g1.y + b1.y); o.w = pk2((bf_lo(v.w) - mu) * rs * g1.z + b1.z, (bf_hi(v.w) - mu) * rs * g1.w + b1.w);
;             *(LAS u32x4*)(lds + SG_B + (cc >> 4) * 32768 + off_b(row, cc & 15)) = o; }
.LBB0_107:
	s_or_b64 exec, exec, s[12:13]
	s_lshl_b32 s30, s2, 7
	s_waitcnt lgkmcnt(0)
	s_lshl_b32 s4, s2, 8
	s_add_i32 s5, 0, 0x20800
	v_lshlrev_b32_e32 v51, 16, v46
	v_and_b32_e32 v46, 0xffff0000, v46
	s_lshl_b32 s12, s4, 1
	s_mov_b32 s13, s31
	s_add_i32 s16, s16, s62
	s_cmpk_gt_i32 s16, 0x3ff
	s_waitcnt vmcnt(0) lgkmcnt(0)
	ds_write_b128 v211, v[82:85]
	ds_write_b128 v212, v[86:89]
	ds_write_b128 v213, v[90:93]
	ds_write_b128 v214, v[94:97]
	v_or_b32_e32 v22, s4, v187
	v_lshlrev_b32_e32 v50, 2, v22
	v_lshlrev_b32_e32 v22, 3, v138
	v_add_u32_e32 v22, s5, v22
	s_waitcnt lgkmcnt(0)
	s_barrier
	ds_read_b64 v[52:53], v22
	global_load_dwordx4 v[22:25], v50, s[44:45] offset:16
	global_load_dwordx4 v[34:37], v50, s[44:45]
	global_load_dwordx4 v[30:33], v50, s[46:47] offset:16
	global_load_dwordx4 v[38:41], v50, s[46:47]
	s_waitcnt lgkmcnt(0)
	v_sub_f32_e32 v51, v51, v52
	v_sub_f32_e32 v46, v46, v52
	v_mul_f32_e32 v51, v53, v51
	v_mul_f32_e32 v46, v53, v46
	s_waitcnt vmcnt(0)
	v_fma_f32 v51, v51, v34, v38
	v_fma_f32 v46, v46, v35, v39
	v_cvt_pk_bf16_f32 v46, v51, v46
	v_lshlrev_b32_e32 v51, 16, v47
	v_and_b32_e32 v47, 0xffff0000, v47
	v_sub_f32_e32 v51, v51, v52
	v_sub_f32_e32 v47, v47, v52
	v_mul_f32_e32 v51, v53, v51
	v_mul_f32_e32 v47, v53, v47
	v_fma_f32 v51, v51, v36, v40
	v_fma_f32 v47, v47, v37, v41
	v_cvt_pk_bf16_f32 v47, v51, v47
	v_lshlrev_b32_e32 v51, 16, v48
	v_and_b32_e32 v48, 0xffff0000, v48
	v_sub_f32_e32 v51, v51, v52
	v_sub_f32_e32 v48, v48, v52
	v_mul_f32_e32 v51, v53, v51
	v_mul_f32_e32 v48, v53, v48
	v_fma_f32 v51, v51, v22, v30
	v_fma_f32 v48, v48, v23, v31
	v_cvt_pk_bf16_f32 v48, v51, v48
	v_lshlrev_b32_e32 v51, 16, v49
	v_and_b32_e32 v49, 0xffff0000, v49
	v_sub_f32_e32 v49, v49, v52
	v_sub_f32_e32 v51, v51, v52
	v_mul_f32_e32 v49, v53, v49
	v_mul_f32_e32 v51, v53, v51
	v_fma_f32 v49, v49, v25, v33
	v_fma_f32 v51, v51, v24, v32
	v_cvt_pk_bf16_f32 v49, v51, v49
	ds_write_b128 v215, v[46:49] offset:32768
	v_lshlrev_b32_e32 v46, 3, v140
	v_add_u32_e32 v46, s5, v46
	ds_read_b64 v[46:47], v46
	v_lshlrev_b32_e32 v48, 16, v42
	v_and_b32_e32 v42, 0xffff0000, v42
	s_waitcnt lgkmcnt(0)
	v_sub_f32_e32 v48, v48, v46
	v_sub_f32_e32 v42, v42, v46
	v_mul_f32_e32 v48, v47, v48
	v_mul_f32_e32 v42, v47, v42
	v_fma_f32 v48, v48, v34, v38
	v_fma_f32 v42, v42, v35, v39
	v_cvt_pk_bf16_f32 v42, v48, v42
	v_lshlrev_b32_e32 v48, 16, v43
	v_and_b32_e32 v43, 0xffff0000, v43
	v_sub_f32_e32 v48, v48, v46
	v_sub_f32_e32 v43, v43, v46
	v_mul_f32_e32 v48, v47, v48
	v_mul_f32_e32 v43, v47, v43
	v_fma_f32 v48, v48, v36, v40
	v_fma_f32 v43, v43, v37, v41
	v_cvt_pk_bf16_f32 v43, v48, v43
	v_lshlrev_b32_e32 v48, 16, v44
	v_and_b32_e32 v44, 0xffff0000, v44
	v_sub_f32_e32 v48, v48, v46
	v_sub_f32_e32 v44, v44, v46
	v_mul_f32_e32 v48, v47, v48
	v_mul_f32_e32 v44, v47, v44
	v_fma_f32 v48, v48, v22, v30
	v_fma_f32 v44, v44, v23, v31
	v_cvt_pk_bf16_f32 v44, v48, v44
	v_lshlrev_b32_e32 v48, 16, v45
	v_and_b32_e32 v45, 0xffff0000, v45
	v_sub_f32_e32 v45, v45, v46
	v_sub_f32_e32 v48, v48, v46
	v_mul_f32_e32 v45, v47, v45
	v_mul_f32_e32 v48, v47, v48
	v_fma_f32 v45, v45, v25, v33
	v_fma_f32 v48, v48, v24, v32
	v_cvt_pk_bf16_f32 v45, v48, v45
	ds_write_b128 v216, v[42:45] offset:32768
	v_add_u32_e32 v42, s5, v0
	ds_read_b64 v[42:43], v42
	v_lshlrev_b32_e32 v44, 16, v26
	v_and_b32_e32 v26, 0xffff0000, v26
	s_waitcnt lgkmcnt(0)
	v_sub_f32_e32 v44, v44, v42
	v_sub_f32_e32 v26, v26, v42
	v_mul_f32_e32 v44, v43, v44
	v_mul_f32_e32 v26, v43, v26
	v_fma_f32 v44, v44, v34, v38
	v_fma_f32 v26, v26, v35, v39
	v_cvt_pk_bf16_f32 v26, v44, v26
	v_lshlrev_b32_e32 v44, 16, v27
	v_and_b32_e32 v27, 0xffff0000, v27
	v_sub_f32_e32 v44, v44, v42
	v_sub_f32_e32 v27, v27, v42
	v_mul_f32_e32 v44, v43, v44
	v_mul_f32_e32 v27, v43, v27
	v_fma_f32 v44, v44, v36, v40
	v_fma_f32 v27, v27, v37, v41
	v_cvt_pk_bf16_f32 v27, v44, v27
	v_lshlrev_b32_e32 v44, 16, v28
	v_and_b32_e32 v28, 0xffff0000, v28
	v_sub_f32_e32 v44, v44, v42
	v_sub_f32_e32 v28, v28, v42
	v_mul_f32_e32 v44, v43, v44
	v_mul_f32_e32 v28, v43, v28
	v_fma_f32 v44, v44, v22, v30
	v_fma_f32 v28, v28, v23, v31
	v_cvt_pk_bf16_f32 v28, v44, v28
	v_lshlrev_b32_e32 v44, 16, v29
	v_and_b32_e32 v29, 0xffff0000, v29
	v_sub_f32_e32 v29, v29, v42
	v_sub_f32_e32 v44, v44, v42
	v_mul_f32_e32 v29, v43, v29
	v_mul_f32_e32 v44, v43, v44
	v_fma_f32 v29, v29, v25, v33
	v_fma_f32 v44, v44, v24, v32
	v_cvt_pk_bf16_f32 v29, v44, v29
	ds_write_b128 v217, v[26:29] offset:32768
	v_add_u32_e32 v26, s5, v189
	ds_read_b64 v[26:27], v26
	v_lshlrev_b32_e32 v28, 16, v18
	v_and_b32_e32 v18, 0xffff0000, v18
	s_waitcnt lgkmcnt(0)
	v_sub_f32_e32 v28, v28, v26
	v_sub_f32_e32 v18, v18, v26
	v_mul_f32_e32 v28, v27, v28
	v_mul_f32_e32 v18, v27, v18
	v_fma_f32 v28, v28, v34, v38
	v_fma_f32 v18, v18, v35, v39
	v_cvt_pk_bf16_f32 v18, v28, v18
	v_lshlrev_b32_e32 v28, 16, v19
	v_and_b32_e32 v19, 0xffff0000, v19
	v_sub_f32_e32 v28, v28, v26
	v_sub_f32_e32 v19, v19, v26
	v_mul_f32_e32 v28, v27, v28
	v_mul_f32_e32 v19, v27, v19
	v_fma_f32 v28, v28, v36, v40
	v_fma_f32 v19, v19, v37, v41
	v_cvt_pk_bf16_f32 v19, v28, v19
	v_lshlrev_b32_e32 v28, 16, v20
	v_and_b32_e32 v20, 0xffff0000, v20
	v_sub_f32_e32 v28, v28, v26
	v_sub_f32_e32 v20, v20, v26
	v_mul_f32_e32 v28, v27, v28
	v_mul_f32_e32 v20, v27, v20
	v_fma_f32 v28, v28, v22, v30
	v_fma_f32 v20, v20, v23, v31
	v_cvt_pk_bf16_f32 v20, v28, v20
	v_lshlrev_b32_e32 v28, 16, v21
	v_and_b32_e32 v21, 0xffff0000, v21
	v_sub_f32_e32 v21, v21, v26
	v_sub_f32_e32 v28, v28, v26
	v_mul_f32_e32 v21, v27, v21
	v_mul_f32_e32 v28, v27, v28
	v_fma_f32 v21, v21, v25, v33
	v_fma_f32 v28, v28, v24, v32
	v_cvt_pk_bf16_f32 v21, v28, v21
	ds_write_b128 v218, v[18:21] offset:32768
	v_add_u32_e32 v18, s5, v190
	ds_read_b64 v[18:19], v18
	v_lshlrev_b32_e32 v20, 16, v14
	v_and_b32_e32 v14, 0xffff0000, v14
	v_lshlrev_b32_e32 v28, 16, v6
	v_and_b32_e32 v6, 0xffff0000, v6
	s_waitcnt lgkmcnt(0)
; #define LAS __attribute__((address_space(3)))
; __device__ __forceinline__ unsigned pk2(float lo, float hi) { unsigned r; asm("v_cvt_pk_bf16_f32 %0, %1, %2" : "=v"(r) : "v"(lo), "v"(hi)); return r; }
; __device__ __forceinline__ float bf_lo(unsigned u) { return __uint_as_float(u << 16); }
; __device__ __forceinline__ float bf_hi(unsigned u) { return __uint_as_float(u & 0xffff0000u); }
; __device__ __forceinline__ void phase_sgu(const Params& P, LAS unsigned char* lds, int layer_i) {
;     ...
;         for (int i = 0; i < 8; ++i) { const int n = tid + 512 * i, row = n >> 5, cc = n & 31, c0 = g * 256 + cc * 8;
;             const u32x4 v = gvr[i];
;             const float mu = st[2 * row], rs = st[2 * row + 1];
;             const f32x4 g0 = *(const f32x4*)(lng + c0), g1 = *(const f32x4*)(lng + c0 + 4), b0 = *(const f32x4*)(lnb + c0), b1 = *(const f32x4*)(lnb + c0 + 4);
;             u32x4 o;
;             o.x = pk2((bf_lo(v.x) - mu) * rs * g0.x + b0.x, (bf_hi(v.x) - mu) * rs * g0.y + b0.y); o.y = pk2((bf_lo(v.y) - mu) * rs * g0.z + b0.z, (bf_hi(v.y) - mu) * rs * g0.w + b0.w);
;             o.z = pk2((bf_lo(v.z) - mu) * rs * g1.x + b1.x, (bf_hi(v.z) - mu) * rs * g1.y + b1.y); o.w = pk2((bf_lo(v.w) - mu) * rs * g1.z + b1.z, (bf_hi(v.w) - mu) * rs * g1.w + b1.w);
;             *(LAS u32x4*)(lds + SG_B + (cc >> 4) * 32768 + off_b(row, cc & 15)) = o; }
;         __syncthreads();
	v_sub_f32_e32 v20, v20, v18
	v_sub_f32_e32 v14, v14, v18
	v_mul_f32_e32 v20, v19, v20
	v_mul_f32_e32 v14, v19, v14
	v_fma_f32 v20, v20, v34, v38
	v_fma_f32 v14, v14, v35, v39
	v_cvt_pk_bf16_f32 v14, v20, v14
	v_lshlrev_b32_e32 v20, 16, v15
	v_and_b32_e32 v15, 0xffff0000, v15
	v_sub_f32_e32 v20, v20, v18
	v_sub_f32_e32 v15, v15, v18
	v_mul_f32_e32 v20, v19, v20
	v_mul_f32_e32 v15, v19, v15
	v_fma_f32 v20, v20, v36, v40
	v_fma_f32 v15, v15, v37, v41
	v_cvt_pk_bf16_f32 v15, v20, v15
	v_lshlrev_b32_e32 v20, 16, v16
	v_and_b32_e32 v16, 0xffff0000, v16
	v_sub_f32_e32 v20, v20, v18
	v_sub_f32_e32 v16, v16, v18
	v_mul_f32_e32 v20, v19, v20
	v_mul_f32_e32 v16, v19, v16
	v_fma_f32 v20, v20, v22, v30
	v_fma_f32 v16, v16, v23, v31
	v_cvt_pk_bf16_f32 v16, v20, v16
	v_lshlrev_b32_e32 v20, 16, v17
	v_and_b32_e32 v17, 0xffff0000, v17
	v_sub_f32_e32 v17, v17, v18
	v_sub_f32_e32 v20, v20, v18
	v_mul_f32_e32 v17, v19, v17
	v_mul_f32_e32 v20, v19, v20
	v_fma_f32 v17, v17, v25, v33
	v_fma_f32 v20, v20, v24, v32
	v_cvt_pk_bf16_f32 v17, v20, v17
	ds_write_b128 v219, v[14:17] offset:32768
	v_add_u32_e32 v14, s5, v191
	ds_read_b64 v[14:15], v14
	v_lshlrev_b32_e32 v16, 16, v10
	v_and_b32_e32 v10, 0xffff0000, v10
	s_waitcnt lgkmcnt(0)
	v_sub_f32_e32 v16, v16, v14
	v_sub_f32_e32 v10, v10, v14
	v_mul_f32_e32 v16, v15, v16
	v_mul_f32_e32 v10, v15, v10
	v_fma_f32 v16, v16, v34, v38
	v_fma_f32 v10, v10, v35, v39
	v_cvt_pk_bf16_f32 v10, v16, v10
	v_lshlrev_b32_e32 v16, 16, v11
	v_sub_f32_e32 v16, v16, v14
	v_and_b32_e32 v11, 0xffff0000, v11
	v_mul_f32_e32 v16, v15, v16
	v_sub_f32_e32 v11, v11, v14
	v_fma_f32 v16, v16, v36, v40
	v_mul_f32_e32 v11, v15, v11
	v_fmac_f32_e32 v41, v11, v37
	v_cvt_pk_bf16_f32 v11, v16, v41
	v_lshlrev_b32_e32 v16, 16, v12
	v_and_b32_e32 v12, 0xffff0000, v12
	v_sub_f32_e32 v16, v16, v14
	v_sub_f32_e32 v12, v12, v14
	v_mul_f32_e32 v16, v15, v16
	v_mul_f32_e32 v12, v15, v12
	v_fma_f32 v16, v16, v22, v30
	v_fma_f32 v12, v12, v23, v31
	v_cvt_pk_bf16_f32 v12, v16, v12
	v_lshlrev_b32_e32 v16, 16, v13
	v_and_b32_e32 v13, 0xffff0000, v13
	v_sub_f32_e32 v16, v16, v14
	v_sub_f32_e32 v13, v13, v14
	v_mul_f32_e32 v16, v15, v16
	v_mul_f32_e32 v13, v15, v13
	v_fma_f32 v16, v16, v24, v32
	v_fmac_f32_e32 v33, v13, v25
	v_cvt_pk_bf16_f32 v13, v16, v33
	ds_write_b128 v220, v[10:13] offset:32768
	v_add_u32_e32 v10, s5, v192
	ds_read_b64 v[26:27], v10
	global_load_dwordx4 v[10:13], v50, s[44:45] offset:16
	global_load_dwordx4 v[18:21], v50, s[44:45]
	global_load_dwordx4 v[14:17], v50, s[46:47] offset:16
	global_load_dwordx4 v[22:25], v50, s[46:47]
	s_waitcnt lgkmcnt(0)
	v_sub_f32_e32 v28, v28, v26
	v_sub_f32_e32 v6, v6, v26
	v_mul_f32_e32 v28, v27, v28
	v_mul_f32_e32 v6, v27, v6
	s_waitcnt vmcnt(0)
	v_fma_f32 v28, v28, v18, v22
	v_fma_f32 v6, v6, v19, v23
	v_cvt_pk_bf16_f32 v6, v28, v6
	v_lshlrev_b32_e32 v28, 16, v7
	v_and_b32_e32 v7, 0xffff0000, v7
	v_sub_f32_e32 v28, v28, v26
	v_sub_f32_e32 v7, v7, v26
	v_mul_f32_e32 v28, v27, v28
	v_mul_f32_e32 v7, v27, v7
	v_fma_f32 v28, v28, v20, v24
	v_fma_f32 v7, v7, v21, v25
	v_cvt_pk_bf16_f32 v7, v28, v7
	v_lshlrev_b32_e32 v28, 16, v8
	v_and_b32_e32 v8, 0xffff0000, v8
	v_sub_f32_e32 v28, v28, v26
	v_sub_f32_e32 v8, v8, v26
	v_mul_f32_e32 v28, v27, v28
	v_mul_f32_e32 v8, v27, v8
	v_fma_f32 v28, v28, v10, v14
	v_fma_f32 v8, v8, v11, v15
	v_cvt_pk_bf16_f32 v8, v28, v8
	v_lshlrev_b32_e32 v28, 16, v9
	v_and_b32_e32 v9, 0xffff0000, v9
	v_sub_f32_e32 v9, v9, v26
	v_sub_f32_e32 v28, v28, v26
	v_mul_f32_e32 v9, v27, v9
	v_mul_f32_e32 v28, v27, v28
	v_fma_f32 v9, v9, v13, v17
	v_fma_f32 v28, v28, v12, v16
	v_cvt_pk_bf16_f32 v9, v28, v9
	ds_write_b128 v221, v[6:9] offset:32768
	v_add_u32_e32 v6, s5, v193
	ds_read_b64 v[6:7], v6
	v_lshlrev_b32_e32 v8, 16, v2
	v_and_b32_e32 v2, 0xffff0000, v2
	s_waitcnt lgkmcnt(0)
	v_sub_f32_e32 v8, v8, v6
	v_sub_f32_e32 v2, v2, v6
	v_mul_f32_e32 v8, v7, v8
	v_mul_f32_e32 v2, v7, v2
	v_fma_f32 v8, v8, v18, v22
	v_fma_f32 v2, v2, v19, v23
	v_cvt_pk_bf16_f32 v2, v8, v2
	v_lshlrev_b32_e32 v8, 16, v3
	v_sub_f32_e32 v8, v8, v6
	v_and_b32_e32 v3, 0xffff0000, v3
	v_mul_f32_e32 v8, v7, v8
	v_sub_f32_e32 v3, v3, v6
	v_fma_f32 v8, v8, v20, v24
	v_mul_f32_e32 v3, v7, v3
	v_fmac_f32_e32 v25, v3, v21
	v_cvt_pk_bf16_f32 v3, v8, v25
	v_lshlrev_b32_e32 v8, 16, v4
	v_and_b32_e32 v4, 0xffff0000, v4
	v_sub_f32_e32 v8, v8, v6
	v_sub_f32_e32 v4, v4, v6
	v_mul_f32_e32 v8, v7, v8
	v_mul_f32_e32 v4, v7, v4
	v_fma_f32 v8, v8, v10, v14
	v_fma_f32 v4, v4, v11, v15
	v_cvt_pk_bf16_f32 v4, v8, v4
	v_lshlrev_b32_e32 v8, 16, v5
	v_and_b32_e32 v5, 0xffff0000, v5
	v_sub_f32_e32 v8, v8, v6
	v_sub_f32_e32 v5, v5, v6
	v_mul_f32_e32 v8, v7, v8
	v_mul_f32_e32 v5, v7, v5
	v_fma_f32 v8, v8, v12, v16
	v_fmac_f32_e32 v17, v5, v13
	v_cvt_pk_bf16_f32 v5, v8, v17
	ds_write_b128 v222, v[2:5] offset:32768
	v_lshl_add_u64 v[2:3], v[134:135], 0, s[12:13]
	v_lshl_add_u64 v[4:5], v[2:3], 0, v[176:177]
	s_waitcnt lgkmcnt(0)
	s_barrier
; #define LAS __attribute__((address_space(3)))
; __device__ __forceinline__ u16x4 tr_read(unsigned lds_addr) { u16x4 r; asm volatile("ds_read_b64_tr_b16 %0, %1\n\ts_waitcnt lgkmcnt(0)" : "=&v"(r) : "v"(lds_addr) : "memory"); return r; }
; #define MFMA32(a, b, c) __builtin_amdgcn_mfma_f32_32x32x16_bf16((a), (b), (c), 0, 0, 0)
; __device__ __forceinline__ void phase_sgu(const Params& P, LAS unsigned char* lds, int layer_i) {
;     ...
;         u32x4 uzr[8];
; #pragma unroll
;         for (int i = 0; i < 8; ++i) { const int n = tid + 512 * i, row = n >> 5, cc = n & 31; uzr[i] = *(const u32x4*)(uz + (row0 + row) * DM + g * 256 + cc * 8); }
;         const unsigned h = lane >> 5, blk = (lane >> 4) & 1, qq = (lane & 15) >> 2, pp = lane & 3;
;         const unsigned bimg = lbase + SG_B + (wave >> 2) * 32768; const int ct = wave & 3;
;         bf16x8 bf[8];
; #pragma unroll
;         for (int ks = 0; ks < 8; ++ks) {
;             const u16x4 t0 = tr_read(bimg + off_b(16 * ks + 8 * h + qq, 4 * ct + 2 * blk + (pp >> 1)) + 8 * (pp & 1));
;             const u16x4 t1 = tr_read(bimg + off_b(16 * ks + 8 * h + 4 + qq, 4 * ct + 2 * blk + (pp >> 1)) + 8 * (pp & 1));
;             bf[ks] = cat4(t0, t1); }
;         f32x16 acc[4];
; #pragma unroll
;         for (int tt = 0; tt < 4; ++tt) {
; #pragma unroll
;             for (int i = 0; i < 16; ++i) acc[tt][i] = 0.f;
; #pragma unroll
;             for (int ks = 0; ks < 8; ++ks) { const bf16x8 af = *(const LAS bf16x8*)(lds + SG_A + off_b(32 * tt + (lane & 31), 2 * ks + h)); acc[tt] = MFMA32(af, bf[ks], acc[tt]); }
;         }
	flat_load_dwordx4 v[82:85], v[4:5]
	v_lshl_add_u64 v[4:5], v[2:3], 0, v[174:175]
	flat_load_dwordx4 v[74:77], v[4:5]
	v_lshl_add_u64 v[4:5], v[2:3], 0, v[172:173]
	flat_load_dwordx4 v[70:73], v[4:5]
	v_lshl_add_u64 v[4:5], v[2:3], 0, v[170:171]
	flat_load_dwordx4 v[66:69], v[4:5]
	v_lshl_add_u64 v[4:5], v[2:3], 0, v[168:169]
	flat_load_dwordx4 v[90:93], v[4:5]
	v_lshl_add_u64 v[4:5], v[2:3], 0, v[166:167]
	flat_load_dwordx4 v[86:89], v[4:5]
	v_lshl_add_u64 v[4:5], v[2:3], 0, v[164:165]
	v_lshl_add_u64 v[2:3], v[2:3], 0, v[162:163]
	flat_load_dwordx4 v[78:81], v[4:5]
	flat_load_dwordx4 v[94:97], v[2:3]
	ds_read_b64_tr_b16 v[2:3], v194
	s_waitcnt lgkmcnt(0)
	ds_read_b64_tr_b16 v[4:5], v195
	s_waitcnt lgkmcnt(0)
	ds_read_b64_tr_b16 v[122:123], v196
	s_waitcnt lgkmcnt(0)
	ds_read_b64_tr_b16 v[124:125], v197
	s_waitcnt lgkmcnt(0)
	ds_read_b64_tr_b16 v[118:119], v198
	s_waitcnt lgkmcnt(0)
	ds_read_b64_tr_b16 v[120:121], v199
	s_waitcnt lgkmcnt(0)
	ds_read_b64_tr_b16 v[114:115], v200
	s_waitcnt lgkmcnt(0)
	ds_read_b64_tr_b16 v[116:117], v201
	s_waitcnt lgkmcnt(0)
	ds_read_b64_tr_b16 v[110:111], v202
	s_waitcnt lgkmcnt(0)
	ds_read_b64_tr_b16 v[112:113], v203
	s_waitcnt lgkmcnt(0)
	ds_read_b64_tr_b16 v[98:99], v204
	s_waitcnt lgkmcnt(0)
	ds_read_b64_tr_b16 v[100:101], v205
	s_waitcnt lgkmcnt(0)
	ds_read_b64_tr_b16 v[102:103], v206
	s_waitcnt lgkmcnt(0)
	ds_read_b64_tr_b16 v[104:105], v207
	s_waitcnt lgkmcnt(0)
	ds_read_b64_tr_b16 v[106:107], v208
	s_waitcnt lgkmcnt(0)
	ds_read_b64_tr_b16 v[108:109], v209
	s_waitcnt lgkmcnt(0)
	ds_read_b128 v[6:9], v223
	ds_read_b128 v[248:251], v224 offset:24576
	s_waitcnt lgkmcnt(0)
	v_mfma_f32_32x32x16_bf16 v[50:65], v[6:9], v[2:5], 0
	ds_read_b128 v[6:9], v224
	s_waitcnt lgkmcnt(0)
	v_mfma_f32_32x32x16_bf16 v[50:65], v[6:9], v[122:125], v[50:65]
	ds_read_b128 v[6:9], v225
	s_waitcnt lgkmcnt(0)
	v_mfma_f32_32x32x16_bf16 v[50:65], v[6:9], v[118:121], v[50:65]
	ds_read_b128 v[6:9], v226
	s_waitcnt lgkmcnt(0)
	v_mfma_f32_32x32x16_bf16 v[50:65], v[6:9], v[114:117], v[50:65]
	ds_read_b128 v[6:9], v227
	s_waitcnt lgkmcnt(0)
	v_mfma_f32_32x32x16_bf16 v[50:65], v[6:9], v[110:113], v[50:65]
	ds_read_b128 v[6:9], v228
	s_waitcnt lgkmcnt(0)
	v_mfma_f32_32x32x16_bf16 v[50:65], v[6:9], v[98:101], v[50:65]
	ds_read_b128 v[6:9], v229
	s_waitcnt lgkmcnt(0)
	v_mfma_f32_32x32x16_bf16 v[50:65], v[6:9], v[102:105], v[50:65]
	ds_read_b128 v[6:9], v230
	s_waitcnt lgkmcnt(0)
	v_mfma_f32_32x32x16_bf16 v[50:65], v[6:9], v[106:109], v[50:65]
	ds_read_b128 v[6:9], v223 offset:8192
	s_waitcnt lgkmcnt(0)
	v_mfma_f32_32x32x16_bf16 v[34:49], v[6:9], v[2:5], 0
	ds_read_b128 v[6:9], v224 offset:8192
	s_waitcnt lgkmcnt(0)
	v_mfma_f32_32x32x16_bf16 v[34:49], v[6:9], v[122:125], v[34:49]
	ds_read_b128 v[6:9], v225 offset:8192
	s_waitcnt lgkmcnt(0)
	v_mfma_f32_32x32x16_bf16 v[34:49], v[6:9], v[118:121], v[34:49]
	ds_read_b128 v[6:9], v226 offset:8192
	s_waitcnt lgkmcnt(0)
	v_mfma_f32_32x32x16_bf16 v[34:49], v[6:9], v[114:117], v[34:49]
	ds_read_b128 v[6:9], v227 offset:8192
	s_waitcnt lgkmcnt(0)
	v_mfma_f32_32x32x16_bf16 v[34:49], v[6:9], v[110:113], v[34:49]
	ds_read_b128 v[6:9], v228 offset:8192
	s_waitcnt lgkmcnt(0)
	v_mfma_f32_32x32x16_bf16 v[34:49], v[6:9], v[98:101], v[34:49]
	ds_read_b128 v[6:9], v229 offset:8192
	s_waitcnt lgkmcnt(0)
	v_mfma_f32_32x32x16_bf16 v[34:49], v[6:9], v[102:105], v[34:49]
	ds_read_b128 v[6:9], v230 offset:8192
	s_waitcnt lgkmcnt(0)
	v_mfma_f32_32x32x16_bf16 v[34:49], v[6:9], v[106:109], v[34:49]
	ds_read_b128 v[6:9], v223 offset:16384
	s_waitcnt lgkmcnt(0)
	v_mfma_f32_32x32x16_bf16 v[18:33], v[6:9], v[2:5], 0
	ds_read_b128 v[6:9], v224 offset:16384
	s_waitcnt lgkmcnt(0)
	v_mfma_f32_32x32x16_bf16 v[18:33], v[6:9], v[122:125], v[18:33]
	ds_read_b128 v[6:9], v225 offset:16384
	s_waitcnt lgkmcnt(0)
	v_mfma_f32_32x32x16_bf16 v[18:33], v[6:9], v[118:121], v[18:33]
	ds_read_b128 v[6:9], v226 offset:16384
	s_waitcnt lgkmcnt(0)
	v_mfma_f32_32x32x16_bf16 v[18:33], v[6:9], v[114:117], v[18:33]
	ds_read_b128 v[6:9], v227 offset:16384
	s_waitcnt lgkmcnt(0)
	v_mfma_f32_32x32x16_bf16 v[18:33], v[6:9], v[110:113], v[18:33]
	ds_read_b128 v[6:9], v228 offset:16384
	s_waitcnt lgkmcnt(0)
	v_mfma_f32_32x32x16_bf16 v[18:33], v[6:9], v[98:101], v[18:33]
	ds_read_b128 v[6:9], v229 offset:16384
	s_waitcnt lgkmcnt(0)
	v_mfma_f32_32x32x16_bf16 v[18:33], v[6:9], v[102:105], v[18:33]
	ds_read_b128 v[6:9], v230 offset:16384
	s_waitcnt lgkmcnt(0)
	v_mfma_f32_32x32x16_bf16 v[18:33], v[6:9], v[106:109], v[18:33]
	ds_read_b128 v[6:9], v223 offset:24576
	s_waitcnt lgkmcnt(0)
	v_mfma_f32_32x32x16_bf16 v[2:17], v[6:9], v[2:5], 0
	v_mfma_f32_32x32x16_bf16 v[2:17], v[248:251], v[122:125], v[2:17]
	ds_read_b128 v[122:125], v225 offset:24576
	s_waitcnt lgkmcnt(0)
	v_mfma_f32_32x32x16_bf16 v[2:17], v[122:125], v[118:121], v[2:17]
	ds_read_b128 v[118:121], v226 offset:24576
	s_waitcnt lgkmcnt(0)
	v_mfma_f32_32x32x16_bf16 v[2:17], v[118:121], v[114:117], v[2:17]
	ds_read_b128 v[114:117], v227 offset:24576
	s_waitcnt lgkmcnt(0)
	v_mfma_f32_32x32x16_bf16 v[2:17], v[114:117], v[110:113], v[2:17]
	ds_read_b128 v[110:113], v228 offset:24576
	s_waitcnt lgkmcnt(0)
	v_mfma_f32_32x32x16_bf16 v[2:17], v[110:113], v[98:101], v[2:17]
	ds_read_b128 v[98:101], v229 offset:24576
	s_waitcnt lgkmcnt(0)
	v_mfma_f32_32x32x16_bf16 v[2:17], v[98:101], v[102:105], v[2:17]
	ds_read_b128 v[98:101], v230 offset:24576
	s_waitcnt lgkmcnt(0)
	s_barrier
; #define LAS __attribute__((address_space(3)))
; __device__ __forceinline__ void phase_sgu(const Params& P, LAS unsigned char* lds, int layer_i) {
;     ...
;         __syncthreads();
; #pragma unroll
;         for (int tt = 0; tt < 4; ++tt)
; #pragma unroll
;             for (int i = 0; i < 16; ++i) { const int t = 32 * tt + (i & 3) + 8 * (i >> 2) + 4 * h;
;                 *(LAS float*)(lds + t * SG_MIX_STRIDE + (32 * wave + (lane & 31)) * 4) = acc[tt][i] + bs[g * 128 + t]; }
;         __syncthreads();
	v_mfma_f32_32x32x16_bf16 v[2:17], v[98:101], v[106:109], v[2:17]
	v_or_b32_e32 v98, s30, v188
	v_lshlrev_b32_e32 v98, 2, v98
	global_load_dwordx4 v[100:103], v98, s[48:49]
	s_waitcnt vmcnt(0)
	v_add_f32_e32 v50, v50, v100
	ds_write_b32 v231, v50
	v_add_f32_e32 v50, v51, v101
	ds_write_b32 v232, v50
	v_add_f32_e32 v50, v52, v102
	ds_write_b32 v232, v50 offset:1040
	v_add_f32_e32 v50, v53, v103
	ds_write_b32 v232, v50 offset:2080
	global_load_dwordx4 v[50:53], v98, s[48:49] offset:32
	s_waitcnt vmcnt(0)
	v_add_f32_e32 v50, v54, v50
	ds_write_b32 v232, v50 offset:7280
	v_add_f32_e32 v50, v55, v51
	ds_write_b32 v232, v50 offset:8320
	v_add_f32_e32 v50, v56, v52
	ds_write_b32 v232, v50 offset:9360
	v_add_f32_e32 v50, v57, v53
	ds_write_b32 v233, v50
	global_load_dwordx4 v[50:53], v98, s[48:49] offset:64
	s_waitcnt vmcnt(0)
	v_add_f32_e32 v50, v58, v50
	ds_write_b32 v233, v50 offset:5200
	v_add_f32_e32 v50, v59, v51
	ds_write_b32 v233, v50 offset:6240
	v_add_f32_e32 v50, v60, v52
	ds_write_b32 v233, v50 offset:7280
	v_add_f32_e32 v50, v61, v53
	ds_write_b32 v233, v50 offset:8320
	global_load_dwordx4 v[50:53], v98, s[48:49] offset:96
	s_waitcnt vmcnt(0)
	v_add_f32_e32 v50, v62, v50
	ds_write_b32 v233, v50 offset:13520
	v_add_f32_e32 v50, v63, v51
	ds_write_b32 v234, v50
	v_add_f32_e32 v50, v64, v52
	ds_write_b32 v234, v50 offset:1040
	v_add_f32_e32 v50, v65, v53
	ds_write_b32 v234, v50 offset:2080
	global_load_dwordx4 v[50:53], v98, s[48:49] offset:128
	s_waitcnt vmcnt(0)
	v_add_f32_e32 v34, v34, v50
	ds_write_b32 v234, v34 offset:7280
	v_add_f32_e32 v34, v35, v51
	ds_write_b32 v234, v34 offset:8320
	v_add_f32_e32 v34, v36, v52
	ds_write_b32 v234, v34 offset:9360
	v_add_f32_e32 v34, v37, v53
	ds_write_b32 v235, v34
	global_load_dwordx4 v[34:37], v98, s[48:49] offset:160
	s_waitcnt vmcnt(0)
	v_add_f32_e32 v34, v38, v34
	ds_write_b32 v235, v34 offset:5200
	v_add_f32_e32 v34, v39, v35
	ds_write_b32 v235, v34 offset:6240
	v_add_f32_e32 v34, v40, v36
	ds_write_b32 v235, v34 offset:7280
	v_add_f32_e32 v34, v41, v37
	ds_write_b32 v235, v34 offset:8320
	global_load_dwordx4 v[34:37], v98, s[48:49] offset:192
	s_waitcnt vmcnt(0)
	v_add_f32_e32 v34, v42, v34
	ds_write_b32 v235, v34 offset:13520
	v_add_f32_e32 v34, v43, v35
	ds_write_b32 v236, v34
	v_add_f32_e32 v34, v44, v36
	ds_write_b32 v236, v34 offset:1040
	v_add_f32_e32 v34, v45, v37
	ds_write_b32 v236, v34 offset:2080
	global_load_dwordx4 v[34:37], v98, s[48:49] offset:224
	s_waitcnt vmcnt(0)
	v_add_f32_e32 v34, v46, v34
	ds_write_b32 v236, v34 offset:7280
	v_add_f32_e32 v34, v47, v35
	ds_write_b32 v236, v34 offset:8320
	v_add_f32_e32 v34, v48, v36
	ds_write_b32 v236, v34 offset:9360
	v_add_f32_e32 v34, v49, v37
	ds_write_b32 v237, v34
	global_load_dwordx4 v[34:37], v98, s[48:49] offset:256
	s_waitcnt vmcnt(0)
	v_add_f32_e32 v18, v18, v34
	ds_write_b32 v237, v18 offset:5200
	v_add_f32_e32 v18, v19, v35
	ds_write_b32 v237, v18 offset:6240
	v_add_f32_e32 v18, v20, v36
	ds_write_b32 v237, v18 offset:7280
	v_add_f32_e32 v18, v21, v37
	ds_write_b32 v237, v18 offset:8320
	global_load_dwordx4 v[18:21], v98, s[48:49] offset:288
	s_waitcnt vmcnt(0)
	v_add_f32_e32 v18, v22, v18
	ds_write_b32 v237, v18 offset:13520
	v_add_f32_e32 v18, v23, v19
	ds_write_b32 v237, v18 offset:14560
	v_add_f32_e32 v18, v24, v20
	ds_write_b32 v237, v18 offset:15600
	v_add_f32_e32 v18, v25, v21
	ds_write_b32 v237, v18 offset:16640
	global_load_dwordx4 v[18:21], v98, s[48:49] offset:320
	s_waitcnt vmcnt(0)
	v_add_f32_e32 v18, v26, v18
	ds_write_b32 v237, v18 offset:21840
	v_add_f32_e32 v18, v27, v19
	ds_write_b32 v237, v18 offset:22880
	v_add_f32_e32 v18, v28, v20
	ds_write_b32 v237, v18 offset:23920
	v_add_f32_e32 v18, v29, v21
	ds_write_b32 v237, v18 offset:24960
	global_load_dwordx4 v[18:21], v98, s[48:49] offset:352
	s_waitcnt vmcnt(0)
	v_add_f32_e32 v18, v30, v18
	ds_write_b32 v237, v18 offset:30160
	v_add_f32_e32 v18, v31, v19
	ds_write_b32 v237, v18 offset:31200
	v_add_f32_e32 v18, v32, v20
	ds_write_b32 v237, v18 offset:32240
	v_add_f32_e32 v18, v33, v21
	ds_write_b32 v237, v18 offset:33280
	global_load_dwordx4 v[18:21], v98, s[48:49] offset:384
	s_waitcnt vmcnt(0)
	v_add_f32_e32 v2, v2, v18
	ds_write_b32 v237, v2 offset:38480
	v_add_f32_e32 v2, v3, v19
	ds_write_b32 v237, v2 offset:39520
	v_add_f32_e32 v2, v4, v20
	ds_write_b32 v237, v2 offset:40560
	v_add_f32_e32 v2, v5, v21
	ds_write_b32 v237, v2 offset:41600
	global_load_dwordx4 v[2:5], v98, s[48:49] offset:416
	s_waitcnt vmcnt(0)
	v_add_f32_e32 v2, v6, v2
	ds_write_b32 v237, v2 offset:46800
	v_add_f32_e32 v2, v7, v3
	ds_write_b32 v237, v2 offset:47840
	v_add_f32_e32 v2, v8, v4
	ds_write_b32 v237, v2 offset:48880
	v_add_f32_e32 v2, v9, v5
	ds_write_b32 v237, v2 offset:49920
	global_load_dwordx4 v[2:5], v98, s[48:49] offset:448
	s_waitcnt vmcnt(0)
	v_add_f32_e32 v2, v10, v2
	ds_write_b32 v237, v2 offset:55120
	v_add_f32_e32 v2, v11, v3
	ds_write_b32 v237, v2 offset:56160
	v_add_f32_e32 v2, v12, v4
	ds_write_b32 v237, v2 offset:57200
	v_add_f32_e32 v2, v13, v5
	ds_write_b32 v237, v2 offset:58240
	global_load_dwordx4 v[2:5], v98, s[48:49] offset:480
	v_lshlrev_b32_e32 v12, 16, v82
	v_lshl_add_u64 v[10:11], v[136:137], 0, s[12:13]
	s_waitcnt vmcnt(0)
	v_add_f32_e32 v2, v14, v2
	ds_write_b32 v237, v2 offset:63440
	v_add_f32_e32 v2, v15, v3
	ds_write_b32 v237, v2 offset:64480
	v_add_f32_e32 v2, v16, v4
	ds_write_b32 v237, v2 offset:65520
	v_add_f32_e32 v2, v17, v5
	ds_write_b32 v238, v2 offset:61360
	s_waitcnt lgkmcnt(0)
	s_barrier
; #define LAS __attribute__((address_space(3)))
; __device__ __forceinline__ unsigned pk2(float lo, float hi) { unsigned r; asm("v_cvt_pk_bf16_f32 %0, %1, %2" : "=v"(r) : "v"(lo), "v"(hi)); return r; }
; __device__ __forceinline__ float bf_lo(unsigned u) { return __uint_as_float(u << 16); }
; __device__ __forceinline__ float bf_hi(unsigned u) { return __uint_as_float(u & 0xffff0000u); }
; __device__ __forceinline__ void phase_sgu(const Params& P, LAS unsigned char* lds, int layer_i) {
;     ...
; #pragma unroll
;         for (int i = 0; i < 8; ++i) { const int n = tid + 512 * i, row = n >> 5, cc = n & 31;
;             const f32x4 m0 = *(const LAS f32x4*)(lds + row * SG_MIX_STRIDE + cc * 32), m1 = *(const LAS f32x4*)(lds + row * SG_MIX_STRIDE + cc * 32 + 16);
;             const size_t o = (row0 + row) * DM + g * 256 + cc * 8;
;             const u32x4 u = uzr[i];
;             u32x4 y; y.x = pk2(bf_lo(u.x) * m0.x, bf_hi(u.x) * m0.y); y.y = pk2(bf_lo(u.y) * m0.z, bf_hi(u.y) * m0.w); y.z = pk2(bf_lo(u.z) * m1.x, bf_hi(u.z) * m1.y); y.w = pk2(bf_lo(u.w) * m1.z, bf_hi(u.w) * m1.w);
;             *(u32x4*)(Y + o) = y; }
;         __syncthreads();
;     }
	ds_read_b128 v[2:5], v239
	ds_read_b128 v[6:9], v239 offset:16
	s_waitcnt lgkmcnt(1)
	v_mul_f32_e32 v2, v2, v12
	v_and_b32_e32 v12, 0xffff0000, v82
	v_mul_f32_e32 v3, v3, v12
	v_cvt_pk_bf16_f32 v2, v2, v3
	v_lshlrev_b32_e32 v3, 16, v83
	v_mul_f32_e32 v3, v4, v3
	v_and_b32_e32 v4, 0xffff0000, v83
	v_mul_f32_e32 v4, v5, v4
	v_cvt_pk_bf16_f32 v3, v3, v4
	v_lshlrev_b32_e32 v4, 16, v84
	v_and_b32_e32 v5, 0xffff0000, v84
	s_waitcnt lgkmcnt(0)
	v_mul_f32_e32 v4, v6, v4
	v_mul_f32_e32 v5, v7, v5
	v_cvt_pk_bf16_f32 v4, v4, v5
	v_lshlrev_b32_e32 v5, 16, v85
	v_and_b32_e32 v6, 0xffff0000, v85
	v_mul_f32_e32 v5, v8, v5
	v_mul_f32_e32 v6, v9, v6
	v_cvt_pk_bf16_f32 v5, v5, v6
	v_lshl_add_u64 v[6:7], v[10:11], 0, v[176:177]
	flat_store_dwordx4 v[6:7], v[2:5]
	ds_read_b128 v[2:5], v240
	ds_read_b128 v[6:9], v240 offset:16
	v_lshlrev_b32_e32 v12, 16, v74
	s_waitcnt lgkmcnt(0)
	v_mul_f32_e32 v2, v2, v12
	v_and_b32_e32 v12, 0xffff0000, v74
	v_mul_f32_e32 v3, v3, v12
	v_cvt_pk_bf16_f32 v2, v2, v3
	v_lshlrev_b32_e32 v3, 16, v75
	v_mul_f32_e32 v3, v4, v3
	v_and_b32_e32 v4, 0xffff0000, v75
	v_mul_f32_e32 v4, v5, v4
	v_cvt_pk_bf16_f32 v3, v3, v4
	v_lshlrev_b32_e32 v4, 16, v76
	v_and_b32_e32 v5, 0xffff0000, v76
	v_mul_f32_e32 v4, v6, v4
	v_mul_f32_e32 v5, v7, v5
	v_cvt_pk_bf16_f32 v4, v4, v5
	v_lshlrev_b32_e32 v5, 16, v77
	v_and_b32_e32 v6, 0xffff0000, v77
	v_mul_f32_e32 v5, v8, v5
	v_mul_f32_e32 v6, v9, v6
	v_cvt_pk_bf16_f32 v5, v5, v6
	v_lshl_add_u64 v[6:7], v[10:11], 0, v[174:175]
	flat_store_dwordx4 v[6:7], v[2:5]
	ds_read_b128 v[2:5], v241
	ds_read_b128 v[6:9], v241 offset:16
	v_lshlrev_b32_e32 v12, 16, v70
	s_waitcnt lgkmcnt(0)
	v_mul_f32_e32 v2, v2, v12
	v_and_b32_e32 v12, 0xffff0000, v70
	v_mul_f32_e32 v3, v3, v12
	v_cvt_pk_bf16_f32 v2, v2, v3
	v_lshlrev_b32_e32 v3, 16, v71
	v_mul_f32_e32 v3, v4, v3
	v_and_b32_e32 v4, 0xffff0000, v71
	v_mul_f32_e32 v4, v5, v4
	v_cvt_pk_bf16_f32 v3, v3, v4
	v_lshlrev_b32_e32 v4, 16, v72
	v_and_b32_e32 v5, 0xffff0000, v72
	v_mul_f32_e32 v4, v6, v4
	v_mul_f32_e32 v5, v7, v5
	v_cvt_pk_bf16_f32 v4, v4, v5
	v_lshlrev_b32_e32 v5, 16, v73
	v_and_b32_e32 v6, 0xffff0000, v73
	v_mul_f32_e32 v5, v8, v5
	v_mul_f32_e32 v6, v9, v6
	v_cvt_pk_bf16_f32 v5, v5, v6
	v_lshl_add_u64 v[6:7], v[10:11], 0, v[172:173]
	flat_store_dwordx4 v[6:7], v[2:5]
	ds_read_b128 v[2:5], v242
	ds_read_b128 v[6:9], v242 offset:16
	v_lshlrev_b32_e32 v12, 16, v66
	s_waitcnt lgkmcnt(0)
	v_mul_f32_e32 v2, v2, v12
	v_and_b32_e32 v12, 0xffff0000, v66
	v_mul_f32_e32 v3, v3, v12
	v_cvt_pk_bf16_f32 v2, v2, v3
	v_lshlrev_b32_e32 v3, 16, v67
	v_mul_f32_e32 v3, v4, v3
	v_and_b32_e32 v4, 0xffff0000, v67
	v_mul_f32_e32 v4, v5, v4
	v_cvt_pk_bf16_f32 v3, v3, v4
	v_lshlrev_b32_e32 v4, 16, v68
	v_and_b32_e32 v5, 0xffff0000, v68
	v_mul_f32_e32 v4, v6, v4
	v_mul_f32_e32 v5, v7, v5
	v_cvt_pk_bf16_f32 v4, v4, v5
	v_lshlrev_b32_e32 v5, 16, v69
	v_and_b32_e32 v6, 0xffff0000, v69
	v_mul_f32_e32 v5, v8, v5
	v_mul_f32_e32 v6, v9, v6
	v_cvt_pk_bf16_f32 v5, v5, v6
	v_lshl_add_u64 v[6:7], v[10:11], 0, v[170:171]
	flat_store_dwordx4 v[6:7], v[2:5]
	ds_read_b128 v[2:5], v243
	ds_read_b128 v[6:9], v243 offset:16
	v_lshlrev_b32_e32 v12, 16, v90
	s_waitcnt lgkmcnt(0)
	v_mul_f32_e32 v2, v2, v12
	v_and_b32_e32 v12, 0xffff0000, v90
	v_mul_f32_e32 v3, v3, v12
	v_cvt_pk_bf16_f32 v2, v2, v3
	v_lshlrev_b32_e32 v3, 16, v91
	v_mul_f32_e32 v3, v4, v3
	v_and_b32_e32 v4, 0xffff0000, v91
	v_mul_f32_e32 v4, v5, v4
	v_cvt_pk_bf16_f32 v3, v3, v4
	v_lshlrev_b32_e32 v4, 16, v92
	v_and_b32_e32 v5, 0xffff0000, v92
	v_mul_f32_e32 v4, v6, v4
	v_mul_f32_e32 v5, v7, v5
	v_cvt_pk_bf16_f32 v4, v4, v5
	v_lshlrev_b32_e32 v5, 16, v93
	v_and_b32_e32 v6, 0xffff0000, v93
	v_mul_f32_e32 v5, v8, v5
	v_mul_f32_e32 v6, v9, v6
	v_cvt_pk_bf16_f32 v5, v5, v6
	v_lshl_add_u64 v[6:7], v[10:11], 0, v[168:169]
	flat_store_dwordx4 v[6:7], v[2:5]
	ds_read_b128 v[2:5], v244
	ds_read_b128 v[6:9], v244 offset:16
	v_lshlrev_b32_e32 v12, 16, v86
	s_waitcnt lgkmcnt(0)
	v_mul_f32_e32 v2, v2, v12
	v_and_b32_e32 v12, 0xffff0000, v86
	v_mul_f32_e32 v3, v3, v12
	v_cvt_pk_bf16_f32 v2, v2, v3
	v_lshlrev_b32_e32 v3, 16, v87
	v_mul_f32_e32 v3, v4, v3
	v_and_b32_e32 v4, 0xffff0000, v87
	v_mul_f32_e32 v4, v5, v4
	v_cvt_pk_bf16_f32 v3, v3, v4
	v_lshlrev_b32_e32 v4, 16, v88
	v_and_b32_e32 v5, 0xffff0000, v88
	v_mul_f32_e32 v4, v6, v4
	v_mul_f32_e32 v5, v7, v5
	v_cvt_pk_bf16_f32 v4, v4, v5
	v_lshlrev_b32_e32 v5, 16, v89
	v_and_b32_e32 v6, 0xffff0000, v89
	v_mul_f32_e32 v5, v8, v5
	v_mul_f32_e32 v6, v9, v6
	v_cvt_pk_bf16_f32 v5, v5, v6
	v_lshl_add_u64 v[6:7], v[10:11], 0, v[166:167]
	flat_store_dwordx4 v[6:7], v[2:5]
	ds_read_b128 v[2:5], v245
	ds_read_b128 v[6:9], v245 offset:16
	v_lshlrev_b32_e32 v12, 16, v78
	s_waitcnt lgkmcnt(0)
	v_mul_f32_e32 v2, v2, v12
	v_and_b32_e32 v12, 0xffff0000, v78
	v_mul_f32_e32 v3, v3, v12
	v_cvt_pk_bf16_f32 v2, v2, v3
	v_lshlrev_b32_e32 v3, 16, v79
	v_mul_f32_e32 v3, v4, v3
	v_and_b32_e32 v4, 0xffff0000, v79
	v_mul_f32_e32 v4, v5, v4
	v_cvt_pk_bf16_f32 v3, v3, v4
	v_lshlrev_b32_e32 v4, 16, v80
	v_and_b32_e32 v5, 0xffff0000, v80
	v_mul_f32_e32 v4, v6, v4
	v_mul_f32_e32 v5, v7, v5
	v_cvt_pk_bf16_f32 v4, v4, v5
	v_lshlrev_b32_e32 v5, 16, v81
	v_and_b32_e32 v6, 0xffff0000, v81
	v_mul_f32_e32 v5, v8, v5
	v_mul_f32_e32 v6, v9, v6
	v_cvt_pk_bf16_f32 v5, v5, v6
	v_lshl_add_u64 v[6:7], v[10:11], 0, v[164:165]
	flat_store_dwordx4 v[6:7], v[2:5]
	ds_read_b128 v[2:5], v246
	ds_read_b128 v[6:9], v246 offset:16
	v_lshlrev_b32_e32 v12, 16, v94
	s_waitcnt lgkmcnt(0)
	v_mul_f32_e32 v2, v2, v12
	v_and_b32_e32 v12, 0xffff0000, v94
	v_mul_f32_e32 v3, v3, v12
	v_cvt_pk_bf16_f32 v2, v2, v3
	v_lshlrev_b32_e32 v3, 16, v95
	v_mul_f32_e32 v3, v4, v3
	v_and_b32_e32 v4, 0xffff0000, v95
	v_mul_f32_e32 v4, v5, v4
	v_cvt_pk_bf16_f32 v3, v3, v4
	v_lshlrev_b32_e32 v4, 16, v96
	v_and_b32_e32 v5, 0xffff0000, v96
	v_mul_f32_e32 v4, v6, v4
	v_mul_f32_e32 v5, v7, v5
	v_cvt_pk_bf16_f32 v4, v4, v5
	v_lshlrev_b32_e32 v5, 16, v97
	v_and_b32_e32 v6, 0xffff0000, v97
	v_mul_f32_e32 v5, v8, v5
	v_mul_f32_e32 v6, v9, v6
	v_cvt_pk_bf16_f32 v5, v5, v6
	v_lshl_add_u64 v[6:7], v[10:11], 0, v[162:163]
	flat_store_dwordx4 v[6:7], v[2:5]
	s_waitcnt lgkmcnt(0)
	s_barrier
	s_cbranch_scc1 .LBB0_110
; #define LAS __attribute__((address_space(3)))
; __device__ __forceinline__ void phase_sgu(const Params& P, LAS unsigned char* lds, int layer_i) {
;     ...
;     for (int item = blockIdx.x; item < (MTOK / 128) * 8; item += gridDim.x) {
;         const int cn = item >> 3, g = item & 7; const size_t row0 = (size_t)cn * 128;
;         u32x4 gvr[8];
; #pragma unroll
;         for (int i = 0; i < 8; ++i) { const int n = tid + 512 * i, row = n >> 5, cc = n & 31; gvr[i] = *(const u32x4*)(gv + (row0 + row) * DM + g * 256 + cc * 8); }
;         { const int rr = tid >> 2, part = tid & 3; const float2* sp = (const float2*)stats + (row0 + rr) * 32 + part * 8; float s1 = 0.f, s2 = 0.f;
; #pragma unroll
;           for (int i = 0; i < 8; ++i) { const float2 v = sp[i]; s1 += v.x; s2 += v.y; }
;           s1 += __shfl_xor(s1, 1); s2 += __shfl_xor(s2, 1); s1 += __shfl_xor(s1, 2); s2 += __shfl_xor(s2, 2);
;           const float mu = s1 * (1.f / DM), var = fmaxf(s2 * (1.f / DM) - mu * mu, 0.f);
;           if (part == 0) { st[2 * rr] = mu; st[2 * rr + 1] = 1.f / sqrtf(var + 1e-6f); } }
; #pragma unroll
;         for (int i = 0; i < 4; ++i) { const int n = tid + 512 * i, row = n >> 4, ch = n & 15;
;             *(LAS u32x4*)(lds + SG_A + off_b(row, ch)) = *(const u32x4*)(wsb + ((size_t)g * 128 + row) * 128 + ch * 8); }
.LBB0_108:
	s_ashr_i32 s4, s16, 3
	s_ashr_i32 s5, s4, 31
	s_and_b32 s2, s16, 7
	s_lshl_b64 s[12:13], s[4:5], 7
	s_lshl_b32 s30, s2, 9
	v_lshl_add_u64 v[4:5], s[12:13], 0, v[138:139]
	v_lshl_add_u64 v[2:3], v[126:127], 0, s[30:31]
	v_lshlrev_b64 v[176:177], 12, v[4:5]
	v_lshl_add_u64 v[4:5], v[2:3], 0, v[176:177]
	global_load_dwordx4 v[46:49], v[4:5], off
	v_lshl_add_u64 v[4:5], s[12:13], 0, v[140:141]
	v_lshlrev_b64 v[174:175], 12, v[4:5]
	v_lshl_add_u64 v[4:5], v[2:3], 0, v[174:175]
	global_load_dwordx4 v[42:45], v[4:5], off
	v_lshl_add_u64 v[4:5], s[12:13], 0, v[142:143]
	v_lshlrev_b64 v[172:173], 12, v[4:5]
	v_lshl_add_u64 v[4:5], v[2:3], 0, v[172:173]
	global_load_dwordx4 v[26:29], v[4:5], off
	v_lshl_add_u64 v[4:5], s[12:13], 0, v[144:145]
	v_lshlrev_b64 v[170:171], 12, v[4:5]
	v_lshl_add_u64 v[4:5], v[2:3], 0, v[170:171]
	global_load_dwordx4 v[18:21], v[4:5], off
	v_lshl_add_u64 v[4:5], s[12:13], 0, v[146:147]
	v_lshlrev_b64 v[168:169], 12, v[4:5]
	v_lshl_add_u64 v[4:5], v[2:3], 0, v[168:169]
	global_load_dwordx4 v[14:17], v[4:5], off
	v_lshl_add_u64 v[4:5], s[12:13], 0, v[148:149]
	v_lshlrev_b64 v[166:167], 12, v[4:5]
	v_lshl_add_u64 v[4:5], v[2:3], 0, v[166:167]
	global_load_dwordx4 v[10:13], v[4:5], off
	v_lshl_add_u64 v[4:5], s[12:13], 0, v[150:151]
	v_lshlrev_b64 v[164:165], 12, v[4:5]
	v_lshl_add_u64 v[4:5], v[2:3], 0, v[164:165]
	global_load_dwordx4 v[6:9], v[4:5], off
	v_lshl_add_u64 v[4:5], s[12:13], 0, v[152:153]
	v_lshl_add_u64 v[22:23], s[12:13], 0, v[128:129]
	v_lshlrev_b64 v[162:163], 12, v[4:5]
	v_lshlrev_b64 v[22:23], 8, v[22:23]
	v_lshl_add_u64 v[2:3], v[2:3], 0, v[162:163]
	v_lshl_add_u64 v[30:31], v[130:131], 0, v[22:23]
	global_load_dwordx4 v[2:5], v[2:3], off
	global_load_dwordx4 v[66:69], v[30:31], off
	global_load_dwordx4 v[70:73], v[30:31], off offset:16
	global_load_dwordx4 v[74:77], v[30:31], off offset:32
	global_load_dwordx4 v[78:81], v[30:31], off offset:48
	s_lshl_b32 s30, s2, 7
	v_lshl_add_u64 v[98:99], s[30:31], 0, v[154:155]
	v_lshlrev_b64 v[98:99], 8, v[98:99]
	v_lshl_add_u64 v[98:99], v[132:133], 0, v[98:99]
	global_load_dwordx4 v[82:85], v[98:99], off
	v_lshl_add_u64 v[98:99], s[30:31], 0, v[156:157]
	v_lshlrev_b64 v[98:99], 8, v[98:99]
	v_lshl_add_u64 v[98:99], v[132:133], 0, v[98:99]
	global_load_dwordx4 v[86:89], v[98:99], off
	v_lshl_add_u64 v[98:99], s[30:31], 0, v[158:159]
	v_lshlrev_b64 v[98:99], 8, v[98:99]
	v_lshl_add_u64 v[98:99], v[132:133], 0, v[98:99]
	global_load_dwordx4 v[90:93], v[98:99], off
	v_lshl_add_u64 v[98:99], s[30:31], 0, v[160:161]
	v_lshlrev_b64 v[98:99], 8, v[98:99]
	v_lshl_add_u64 v[98:99], v[132:133], 0, v[98:99]
	global_load_dwordx4 v[94:97], v[98:99], off
	s_waitcnt vmcnt(4)
	v_add_f32_e32 v22, 0, v66
	v_add_f32_e32 v23, 0, v67
	v_add_f32_e32 v22, v22, v68
	v_add_f32_e32 v23, v23, v69
	v_add_f32_e32 v22, v22, v70
	v_add_f32_e32 v23, v23, v71
	v_add_f32_e32 v22, v22, v72
	v_add_f32_e32 v23, v23, v73
	v_add_f32_e32 v22, v22, v74
	v_add_f32_e32 v23, v23, v75
	v_add_f32_e32 v22, v22, v76
	v_add_f32_e32 v23, v23, v77
	v_add_f32_e32 v22, v22, v78
	v_add_f32_e32 v23, v23, v79
	v_add_f32_e32 v22, v22, v80
	v_add_f32_e32 v23, v23, v81
	ds_bpermute_b32 v24, v185, v22
	s_waitcnt lgkmcnt(0)
	v_add_f32_e32 v22, v22, v24
	ds_bpermute_b32 v24, v185, v23
	s_waitcnt lgkmcnt(0)
	v_add_f32_e32 v23, v23, v24
	ds_bpermute_b32 v24, v186, v22
	ds_bpermute_b32 v25, v186, v23
	s_and_saveexec_b64 s[12:13], s[40:41]
	s_cbranch_execz .LBB0_107
	s_waitcnt lgkmcnt(1)
	v_add_f32_e32 v22, v22, v24
	v_mul_f32_e32 v22, 0x3a000000, v22
	s_waitcnt lgkmcnt(0)
	v_add_f32_e32 v23, v23, v25
	v_mul_f32_e32 v24, v22, v22
	s_mov_b32 s3, 0x3a000000
	v_fma_f32 v23, v23, s3, -v24
	v_max_f32_e32 v23, 0, v23
	v_add_f32_e32 v23, 0x358637bd, v23
	s_mov_b32 s3, 0xf800000
	v_mul_f32_e32 v24, 0x4f800000, v23
	v_cmp_gt_f32_e32 vcc, s3, v23
	s_nop 1
	v_cndmask_b32_e32 v23, v23, v24, vcc
	v_sqrt_f32_e32 v24, v23
	s_nop 0
	v_add_u32_e32 v25, -1, v24
	v_fma_f32 v30, -v25, v24, v23
	v_cmp_ge_f32_e64 s[42:43], 0, v30
	v_add_u32_e32 v30, 1, v24
	s_nop 0
	v_cndmask_b32_e64 v25, v24, v25, s[42:43]
	v_fma_f32 v24, -v30, v24, v23
	v_cmp_lt_f32_e64 s[42:43], 0, v24
	s_nop 1
	v_cndmask_b32_e64 v24, v25, v30, s[42:43]
	v_mul_f32_e32 v25, 0x37800000, v24
	v_cndmask_b32_e32 v24, v24, v25, vcc
	v_cmp_class_f32_e32 vcc, v23, v180
	s_nop 1
	v_cndmask_b32_e32 v23, v24, v23, vcc
	v_div_scale_f32 v24, s[4:5], v23, v23, 1.0
	v_rcp_f32_e32 v25, v24
	s_nop 0
	v_fma_f32 v30, -v24, v25, 1.0
	v_fmac_f32_e32 v25, v30, v25
	v_div_scale_f32 v30, vcc, 1.0, v23, 1.0
	v_mul_f32_e32 v31, v30, v25
	v_fma_f32 v32, -v24, v31, v30
	v_fmac_f32_e32 v31, v32, v25
	v_fma_f32 v24, -v24, v31, v30
	v_div_fmas_f32 v24, v24, v25, v31
	v_div_fixup_f32 v23, v24, v23, 1.0
	ds_write_b64 v210, v[22:23]
	s_branch .LBB0_107
